# GLA scan B2/C: channel-pair arithmetic on packed f32 ops (v_pk_add/mul/fma_f32, bit-identical results, 64 fewer VALU issues per thread-step)
# speedup vs baseline: 1.0091x; 1.0020x over previous
; __device__ __forceinline__ int crow(int r, int hi) { return (r & 3) + 8 * (r >> 2) + 4 * hi; }
; #define OPAQUE_TID(name) int name = MK_TID; asm volatile("" : "+v"(name))
; __device__ __forceinline__ void scan_unit(const int unit, const Args& a, unsigned char* lds, const int mk_wid) {
;     ...
;         { OPAQUE_TID(t_); const int lane = t_ & 63, r32 = lane & 31, hi = lane >> 5; const int tt = wid >> 2, ct = wid & 3;
;           const bf16x8 af = *(const bf16x8*)(lds + L_LR + (tt * 32 + r32) * 32 + hi * 16);
;           const f32x16 z = __builtin_amdgcn_mfma_f32_32x32x16_bf16(af, upf, f32x16{}, 0, 0, 0);
;           float* lw = las + (tt * 32 + 4 * hi) * 128 + ct * 32 + r32;
; #pragma unroll
;           for (int r = 0; r < 16; ++r) { const float zz = z[r] + biasc;
;               lw[crow(r, 0) * 128] = (fminf(zz, 0.f) - __builtin_amdgcn_logf(1.f + __builtin_amdgcn_exp2f(-1.4426950408889634f * fabsf(zz))) * 0.6931471805599453f) * (1.f / 16.f); } }
.Lscan_noflush:
	v_mbcnt_lo_u32_b32 v64, -1, 0
	v_mbcnt_hi_u32_b32 v64, -1, v64
	s_nop 0
	v_add_u32_e32 v64, s72, v64
	s_nop 0
	v_and_b32_e32 v68, 31, v64
	v_bfe_u32 v69, v64, 5, 1
	v_lshlrev_b32_e32 v69, 11, v69
	v_lshlrev_b32_e32 v68, 2, v68
	v_add3_u32 v80, s45, v69, v68
	v_mfma_f32_32x32x16_bf16 v[64:79], v[96:99], v[108:111], 0
	s_nop 11
	v_add_f32_e32 v64, v156, v64
	v_add_f32_e32 v65, v156, v65
	v_mul_f32_e64 v81, |v64|, s54
	v_mul_f32_e64 v82, |v65|, s54
	v_exp_f32_e32 v81, v81
	v_exp_f32_e32 v82, v82
	v_add_f32_e32 v66, v156, v66
	v_min_f32_e32 v64, 0, v64
	v_add_f32_e32 v81, 1.0, v81
	v_add_f32_e32 v82, 1.0, v82
	v_log_f32_e32 v81, v81
	v_log_f32_e32 v82, v82
	v_min_f32_e32 v65, 0, v65
	v_mul_f32_e64 v83, |v66|, s54
	v_fmac_f32_e32 v64, 0xbf317218, v81
	v_fmac_f32_e32 v65, 0xbf317218, v82
	v_add_f32_e32 v67, v156, v67
	v_exp_f32_e32 v83, v83
	v_mul_f32_e32 v64, 0x3db8aa3b, v64
	v_mul_f32_e32 v65, 0x3db8aa3b, v65
	ds_write2st64_b32 v80, v64, v65 offset1:2
	v_mul_f32_e64 v64, |v67|, s54
	v_exp_f32_e32 v64, v64
	v_add_f32_e32 v65, 1.0, v83
	v_log_f32_e32 v65, v65
	v_min_f32_e32 v66, 0, v66
	v_add_f32_e32 v64, 1.0, v64
	v_log_f32_e32 v64, v64
	v_fmac_f32_e32 v66, 0xbf317218, v65
	v_mul_f32_e32 v65, 0x3db8aa3b, v66
	v_min_f32_e32 v66, 0, v67
	v_fmac_f32_e32 v66, 0xbf317218, v64
	v_mul_f32_e32 v64, 0x3db8aa3b, v66
	ds_write2st64_b32 v80, v65, v64 offset0:4 offset1:6
	v_add_f32_e32 v64, v156, v68
	v_mul_f32_e64 v65, |v64|, s54
	v_add_f32_e32 v66, v156, v69
	v_exp_f32_e32 v65, v65
	v_mul_f32_e64 v67, |v66|, s54
	v_exp_f32_e32 v67, v67
	v_min_f32_e32 v64, 0, v64
	v_add_f32_e32 v65, 1.0, v65
	v_log_f32_e32 v65, v65
	v_add_f32_e32 v67, 1.0, v67
	v_log_f32_e32 v67, v67
	v_fmac_f32_e32 v64, 0xbf317218, v65
	v_min_f32_e32 v65, 0, v66
	v_fmac_f32_e32 v65, 0xbf317218, v67
	v_mul_f32_e32 v64, 0x3db8aa3b, v64
	v_mul_f32_e32 v65, 0x3db8aa3b, v65
	ds_write2st64_b32 v80, v64, v65 offset0:16 offset1:18
	v_add_f32_e32 v64, v156, v70
	v_mul_f32_e64 v65, |v64|, s54
	v_add_f32_e32 v66, v156, v71
	v_exp_f32_e32 v65, v65
	v_mul_f32_e64 v67, |v66|, s54
	v_exp_f32_e32 v67, v67
	v_min_f32_e32 v64, 0, v64
	v_add_f32_e32 v65, 1.0, v65
	v_log_f32_e32 v65, v65
	v_add_f32_e32 v67, 1.0, v67
	v_log_f32_e32 v67, v67
	v_fmac_f32_e32 v64, 0xbf317218, v65
	v_min_f32_e32 v65, 0, v66
	v_fmac_f32_e32 v65, 0xbf317218, v67
	v_mul_f32_e32 v64, 0x3db8aa3b, v64
	v_mul_f32_e32 v65, 0x3db8aa3b, v65
	ds_write2st64_b32 v80, v64, v65 offset0:20 offset1:22
	v_add_f32_e32 v64, v156, v72
	v_mul_f32_e64 v65, |v64|, s54
	v_add_f32_e32 v66, v156, v73
	v_exp_f32_e32 v65, v65
	v_mul_f32_e64 v67, |v66|, s54
	v_exp_f32_e32 v67, v67
	v_min_f32_e32 v64, 0, v64
	v_add_f32_e32 v65, 1.0, v65
	v_log_f32_e32 v65, v65
	v_add_f32_e32 v67, 1.0, v67
	v_log_f32_e32 v67, v67
	v_fmac_f32_e32 v64, 0xbf317218, v65
	v_min_f32_e32 v65, 0, v66
	v_fmac_f32_e32 v65, 0xbf317218, v67
	v_mul_f32_e32 v64, 0x3db8aa3b, v64
	v_mul_f32_e32 v65, 0x3db8aa3b, v65
	ds_write2st64_b32 v80, v64, v65 offset0:32 offset1:34
	v_add_f32_e32 v64, v156, v74
	v_mul_f32_e64 v65, |v64|, s54
	v_add_f32_e32 v66, v156, v75
	v_exp_f32_e32 v65, v65
	v_mul_f32_e64 v67, |v66|, s54
	v_exp_f32_e32 v67, v67
	v_min_f32_e32 v64, 0, v64
	v_add_f32_e32 v65, 1.0, v65
	v_log_f32_e32 v65, v65
	v_add_f32_e32 v67, 1.0, v67
	v_log_f32_e32 v67, v67
	v_fmac_f32_e32 v64, 0xbf317218, v65
	v_min_f32_e32 v65, 0, v66
	v_fmac_f32_e32 v65, 0xbf317218, v67
	v_mul_f32_e32 v64, 0x3db8aa3b, v64
	v_mul_f32_e32 v65, 0x3db8aa3b, v65
	ds_write2st64_b32 v80, v64, v65 offset0:36 offset1:38
	v_add_f32_e32 v64, v156, v76
	v_mul_f32_e64 v65, |v64|, s54
	v_add_f32_e32 v66, v156, v77
	v_exp_f32_e32 v65, v65
	v_mul_f32_e64 v67, |v66|, s54
	v_exp_f32_e32 v67, v67
	v_min_f32_e32 v64, 0, v64
	v_add_f32_e32 v65, 1.0, v65
	v_log_f32_e32 v65, v65
	v_add_f32_e32 v67, 1.0, v67
	v_log_f32_e32 v67, v67
	v_fmac_f32_e32 v64, 0xbf317218, v65
	v_min_f32_e32 v65, 0, v66
	v_fmac_f32_e32 v65, 0xbf317218, v67
	v_mul_f32_e32 v64, 0x3db8aa3b, v64
	v_mul_f32_e32 v65, 0x3db8aa3b, v65
	ds_write2st64_b32 v80, v64, v65 offset0:48 offset1:50
	v_add_f32_e32 v64, v156, v78
	v_mul_f32_e64 v65, |v64|, s54
	v_add_f32_e32 v66, v156, v79
	v_exp_f32_e32 v65, v65
	v_mul_f32_e64 v67, |v66|, s54
	v_exp_f32_e32 v67, v67
	v_min_f32_e32 v64, 0, v64
	v_add_f32_e32 v65, 1.0, v65
	v_log_f32_e32 v65, v65
	v_add_f32_e32 v67, 1.0, v67
	v_log_f32_e32 v67, v67
	v_fmac_f32_e32 v64, 0xbf317218, v65
	v_min_f32_e32 v65, 0, v66
	v_fmac_f32_e32 v65, 0xbf317218, v67
	v_mul_f32_e32 v64, 0x3db8aa3b, v64
	v_mul_f32_e32 v65, 0x3db8aa3b, v65
	ds_write2st64_b32 v80, v64, v65 offset0:52 offset1:54
	s_waitcnt lgkmcnt(0)
	s_barrier
; __device__ __forceinline__ int v_st(int k, int c) { const int kk = (k & ~0xC) | ((k & 4) << 1) | ((k & 8) >> 1); return ((kk >> 3) * 4 + (c >> 5)) * 512 + ((kk & 7) * 32 + (c & 31)) * 2; }
; __device__ __forceinline__ float bf2f(short s) { return __uint_as_float(((unsigned)(unsigned short)s) << 16); }
; __device__ __forceinline__ float bf2f(u16 u) { return __uint_as_float((unsigned)u << 16); }
; #define OPAQUE_TID(name) int name = MK_TID; asm volatile("" : "+v"(name))
; __device__ __forceinline__ void scan_unit(const int unit, const Args& a, unsigned char* lds, const int mk_wid) {
;     ...
;         { OPAQUE_TID(t_); const int c = t_ & 127, g = t_ >> 7;
;           float bl[16]; float run = 0.f;
;           { const float* lp = las + (g * 16) * 128 + c;
; #pragma unroll
;             for (int ii = 0; ii < 16; ++ii) { run += lp[ii * 128]; bl[ii] = run; } }
;           gs[g * 128 + c] = run;
;           __syncthreads();
;           const float g0 = gs[c], g1 = gs[128 + c], g2 = gs[256 + c], g3 = gs[384 + c];
;           const float off = (g > 0 ? g0 : 0.f) + (g > 1 ? g1 : 0.f) + (g > 2 ? g2 : 0.f);
;           const float btot = (g0 + g1) + (g2 + g3);
;           const float dlc = __builtin_amdgcn_exp2f(btot * 1.4426950408889634f);
;           if (g == 0) dl[c] = dlc;
;           u16* qcol = qe + (g * 16) * QP + c; u16* kcol = ke + (g * 16) * QP + c; unsigned char* kdb = lds + L_KD + v_st(g * 16, c);
; #pragma unroll
;           for (int ii = 0; ii < 16; ++ii) { const float bb = bl[ii] + off;
;               const float qf = bf2f(qcol[ii * QP]), kf = bf2f(kcol[ii * QP]);
;               const float e = __builtin_amdgcn_exp2f(bb * 1.4426950408889634f), ker = kf * __builtin_amdgcn_rcpf(e);
	v_mbcnt_lo_u32_b32 v64, -1, 0
	v_mbcnt_hi_u32_b32 v64, -1, v64
	s_lshl_b32 s96, s70, 12
	s_add_i32 s96, s96, s9
	v_lshl_add_u32 v65, v64, 3, s96
	ds_read_b64 v[170:171], v65
	ds_read_b64 v[172:173], v65 offset:512
	ds_read_b64 v[174:175], v65 offset:1024
	ds_read_b64 v[176:177], v65 offset:1536
	ds_read_b64 v[178:179], v65 offset:2048
	ds_read_b64 v[180:181], v65 offset:2560
	ds_read_b64 v[182:183], v65 offset:3072
	ds_read_b64 v[184:185], v65 offset:3584
	s_cmp_gt_u32 s70, 0
	s_cselect_b32 s97, 1.0, 0
	v_mov_b32_e32 v238, s97
	s_cmp_gt_u32 s70, 1
	s_cselect_b32 s97, 1.0, 0
	v_mov_b32_e32 v239, s97
	s_cmp_gt_u32 s70, 2
	s_cselect_b32 s97, 1.0, 0
	v_mov_b32_e32 v240, s97
	s_cmp_gt_u32 s70, 3
	s_cselect_b32 s97, 1.0, 0
	v_mov_b32_e32 v241, s97
	s_cmp_gt_u32 s70, 4
	s_cselect_b32 s97, 1.0, 0
	v_mov_b32_e32 v242, s97
	s_cmp_gt_u32 s70, 5
	s_cselect_b32 s97, 1.0, 0
	v_mov_b32_e32 v243, s97
	s_cmp_gt_u32 s70, 6
	s_cselect_b32 s97, 1.0, 0
	v_mov_b32_e32 v244, s97
	s_lshl_b32 s98, s70, 9
	s_add_i32 s98, s98, 0x20000
	v_lshl_add_u32 v66, v64, 3, s98
	v_lshlrev_b32_e32 v67, 3, v64
	v_add_u32_e32 v67, 0x20000, v67
	s_mul_i32 s99, s70, 0x880
	v_lshl_add_u32 v68, v64, 2, s99
	v_and_b32_e32 v94, 2, v64
	v_lshlrev_b32_e32 v94, 1, v94
	v_and_b32_e32 v95, 4, v64
	v_lshrrev_b32_e32 v95, 1, v95
	v_and_b32_e32 v70, 0xfffffff9, v64
	v_or3_b32 v94, v94, v95, v70
	v_lshl_add_u32 v94, v94, 2, s99
	s_lshr_b32 s98, s70, 1
	s_lshl_b32 s98, s98, 12
	s_and_b32 s99, s70, 1
	s_lshl_b32 s99, s99, 8
	s_add_i32 s98, s98, s99
	v_lshrrev_b32_e32 v69, 4, v64
	v_lshlrev_b32_e32 v69, 9, v69
	v_and_b32_e32 v70, 15, v64
	v_lshl_add_u32 v69, v70, 2, v69
	v_add_u32_e32 v69, s98, v69
	s_waitcnt lgkmcnt(7)
	s_waitcnt lgkmcnt(6)
	v_pk_add_f32 v[172:173], v[170:171], v[172:173]
	s_waitcnt lgkmcnt(5)
	v_pk_add_f32 v[174:175], v[172:173], v[174:175]
	s_waitcnt lgkmcnt(4)
	v_pk_add_f32 v[176:177], v[174:175], v[176:177]
	s_waitcnt lgkmcnt(3)
	v_pk_add_f32 v[178:179], v[176:177], v[178:179]
	s_waitcnt lgkmcnt(2)
	v_pk_add_f32 v[180:181], v[178:179], v[180:181]
	s_waitcnt lgkmcnt(1)
	v_pk_add_f32 v[182:183], v[180:181], v[182:183]
	s_waitcnt lgkmcnt(0)
	v_pk_add_f32 v[184:185], v[182:183], v[184:185]
	ds_write_b64 v66, v[184:185]
	s_waitcnt lgkmcnt(0)
	s_barrier
	ds_read_b64 v[72:73], v67
	ds_read_b64 v[74:75], v67 offset:512
	ds_read_b64 v[76:77], v67 offset:1024
	ds_read_b64 v[78:79], v67 offset:1536
	ds_read_b64 v[80:81], v67 offset:2048
	ds_read_b64 v[82:83], v67 offset:2560
	ds_read_b64 v[84:85], v67 offset:3072
	ds_read_b64 v[86:87], v67 offset:3584
	s_waitcnt lgkmcnt(0)
	v_pk_mul_f32 v[88:89], v[238:239], v[72:73] op_sel:[0,0] op_sel_hi:[0,1]
	v_pk_fma_f32 v[88:89], v[238:239], v[74:75], v[88:89] op_sel:[1,0,0] op_sel_hi:[1,1,1]
	v_pk_fma_f32 v[88:89], v[240:241], v[76:77], v[88:89] op_sel:[0,0,0] op_sel_hi:[0,1,1]
	v_pk_fma_f32 v[88:89], v[240:241], v[78:79], v[88:89] op_sel:[1,0,0] op_sel_hi:[1,1,1]
	v_pk_fma_f32 v[88:89], v[242:243], v[80:81], v[88:89] op_sel:[0,0,0] op_sel_hi:[0,1,1]
	v_pk_fma_f32 v[88:89], v[242:243], v[82:83], v[88:89] op_sel:[1,0,0] op_sel_hi:[1,1,1]
	v_pk_fma_f32 v[88:89], v[244:245], v[84:85], v[88:89] op_sel:[0,0,0] op_sel_hi:[0,1,1]
	v_pk_add_f32 v[90:91], v[72:73], v[74:75]
	v_pk_add_f32 v[90:91], v[90:91], v[76:77]
	v_pk_add_f32 v[90:91], v[90:91], v[78:79]
	v_pk_add_f32 v[90:91], v[90:91], v[80:81]
	v_pk_add_f32 v[90:91], v[90:91], v[82:83]
	v_pk_add_f32 v[90:91], v[90:91], v[84:85]
	v_pk_add_f32 v[90:91], v[90:91], v[86:87]
	v_mov_b64_e32 v[92:93], v[90:91]
	v_exp_f32_e32 v92, v92
	v_exp_f32_e32 v93, v93
	v_pk_add_f32 v[170:171], v[170:171], v[88:89]
	v_pk_add_f32 v[172:173], v[172:173], v[88:89]
	v_pk_add_f32 v[174:175], v[174:175], v[88:89]
	v_pk_add_f32 v[176:177], v[176:177], v[88:89]
	v_pk_add_f32 v[178:179], v[178:179], v[88:89]
	v_pk_add_f32 v[180:181], v[180:181], v[88:89]
	v_pk_add_f32 v[182:183], v[182:183], v[88:89]
	v_pk_add_f32 v[184:185], v[184:185], v[88:89]
	v_exp_f32_e32 v170, v170
	v_exp_f32_e32 v171, v171
	v_exp_f32_e32 v172, v172
	v_exp_f32_e32 v173, v173
	v_exp_f32_e32 v174, v174
	v_exp_f32_e32 v175, v175
	v_exp_f32_e32 v176, v176
	v_exp_f32_e32 v177, v177
	v_exp_f32_e32 v178, v178
	v_exp_f32_e32 v179, v179
	v_exp_f32_e32 v180, v180
	v_exp_f32_e32 v181, v181
	v_exp_f32_e32 v182, v182
	v_exp_f32_e32 v183, v183
	v_exp_f32_e32 v184, v184
	v_exp_f32_e32 v185, v185
	v_rcp_f32_e32 v186, v170
	v_rcp_f32_e32 v187, v171
	v_rcp_f32_e32 v188, v172
	v_rcp_f32_e32 v189, v173
	v_rcp_f32_e32 v190, v174
	v_rcp_f32_e32 v191, v175
	v_rcp_f32_e32 v192, v176
	v_rcp_f32_e32 v193, v177
	v_rcp_f32_e32 v194, v178
	v_rcp_f32_e32 v195, v179
	v_rcp_f32_e32 v196, v180
	v_rcp_f32_e32 v197, v181
	v_rcp_f32_e32 v198, v182
	v_rcp_f32_e32 v199, v183
	v_rcp_f32_e32 v200, v184
	v_rcp_f32_e32 v201, v185
	s_mov_b32 s96, 0x3db504f3
	s_mov_b32 s97, s96
	v_pk_mul_f32 v[170:171], v[170:171], s[96:97]
	v_pk_mul_f32 v[172:173], v[172:173], s[96:97]
	v_pk_mul_f32 v[174:175], v[174:175], s[96:97]
	v_pk_mul_f32 v[176:177], v[176:177], s[96:97]
	v_pk_mul_f32 v[178:179], v[178:179], s[96:97]
	v_pk_mul_f32 v[180:181], v[180:181], s[96:97]
	v_pk_mul_f32 v[182:183], v[182:183], s[96:97]
	v_pk_mul_f32 v[184:185], v[184:185], s[96:97]
	s_cmp_lg_u32 s70, 0
	s_cbranch_scc1 .Lscan_c2_nodl
	v_lshlrev_b32_e32 v70, 3, v64
	v_add_u32_e32 v70, 0x1fc00, v70
	ds_write_b64 v70, v[92:93]
; __device__ __forceinline__ int v_st(int k, int c) { const int kk = (k & ~0xC) | ((k & 4) << 1) | ((k & 8) >> 1); return ((kk >> 3) * 4 + (c >> 5)) * 512 + ((kk & 7) * 32 + (c & 31)) * 2; }
; __device__ __forceinline__ float bf2f(short s) { return __uint_as_float(((unsigned)(unsigned short)s) << 16); }
; __device__ __forceinline__ float bf2f(u16 u) { return __uint_as_float((unsigned)u << 16); }
; __device__ __forceinline__ u16 f2bf(float f) { return (u16)(pk2(f, 0.f) & 0xffffu); }
; __device__ __forceinline__ void scan_unit(const int unit, const Args& a, unsigned char* lds, const int mk_wid) {
;     ...
;           u16* qcol = qe + (g * 16) * QP + c; u16* kcol = ke + (g * 16) * QP + c; unsigned char* kdb = lds + L_KD + v_st(g * 16, c);
; #pragma unroll
;           for (int ii = 0; ii < 16; ++ii) { const float bb = bl[ii] + off;
;               const float qf = bf2f(qcol[ii * QP]), kf = bf2f(kcol[ii * QP]);
;               const float e = __builtin_amdgcn_exp2f(bb * 1.4426950408889634f), ker = kf * __builtin_amdgcn_rcpf(e);
;               qcol[ii * QP] = f2bf(qf * (0.088388347648318440f * e));
;               kcol[ii * QP] = f2bf(ker);
;               *(u16*)(kdb + v_st(ii, 0)) = f2bf(ker * dlc); } }
.Lscan_c2_nodl:
	v_mov_b32_e32 v71, 0xffff0000
	v_lshlrev_b32_e32 v218, 16, v128
	v_and_b32_e32 v219, v71, v128
	v_lshlrev_b32_e32 v220, 16, v100
	v_and_b32_e32 v221, v71, v100
	v_pk_mul_f32 v[218:219], v[170:171], v[218:219]
	v_pk_mul_f32 v[220:221], v[186:187], v[220:221]
	v_cvt_pk_bf16_f32 v224, v218, v219
	v_pk_mul_f32 v[222:223], v[92:93], v[220:221]
	v_cvt_pk_bf16_f32 v225, v220, v221
	ds_write_b32 v94, v224
	ds_write_b32 v94, v225 offset:17408
	v_cvt_pk_bf16_f32 v226, v222, v223
	ds_write_b32 v69, v226 offset:34816
	v_lshlrev_b32_e32 v228, 16, v129
	v_and_b32_e32 v229, v71, v129
	v_lshlrev_b32_e32 v230, 16, v101
	v_and_b32_e32 v231, v71, v101
	v_pk_mul_f32 v[228:229], v[172:173], v[228:229]
	v_pk_mul_f32 v[230:231], v[188:189], v[230:231]
	v_cvt_pk_bf16_f32 v234, v228, v229
	v_pk_mul_f32 v[232:233], v[92:93], v[230:231]
	v_cvt_pk_bf16_f32 v235, v230, v231
	ds_write_b32 v94, v234 offset:272
	ds_write_b32 v94, v235 offset:17680
	v_cvt_pk_bf16_f32 v236, v232, v233
	ds_write_b32 v69, v236 offset:34880
	v_lshlrev_b32_e32 v218, 16, v130
	v_and_b32_e32 v219, v71, v130
	v_lshlrev_b32_e32 v220, 16, v102
	v_and_b32_e32 v221, v71, v102
	v_pk_mul_f32 v[218:219], v[174:175], v[218:219]
	v_pk_mul_f32 v[220:221], v[190:191], v[220:221]
	v_cvt_pk_bf16_f32 v224, v218, v219
	v_pk_mul_f32 v[222:223], v[92:93], v[220:221]
	v_cvt_pk_bf16_f32 v225, v220, v221
	ds_write_b32 v94, v224 offset:544
	ds_write_b32 v94, v225 offset:17952
	v_cvt_pk_bf16_f32 v226, v222, v223
	ds_write_b32 v69, v226 offset:34944
	v_lshlrev_b32_e32 v228, 16, v131
	v_and_b32_e32 v229, v71, v131
	v_lshlrev_b32_e32 v230, 16, v103
	v_and_b32_e32 v231, v71, v103
	v_pk_mul_f32 v[228:229], v[176:177], v[228:229]
	v_pk_mul_f32 v[230:231], v[192:193], v[230:231]
	v_cvt_pk_bf16_f32 v234, v228, v229
	v_pk_mul_f32 v[232:233], v[92:93], v[230:231]
	v_cvt_pk_bf16_f32 v235, v230, v231
	ds_write_b32 v94, v234 offset:816
	ds_write_b32 v94, v235 offset:18224
	v_cvt_pk_bf16_f32 v236, v232, v233
	ds_write_b32 v69, v236 offset:35008
	v_lshlrev_b32_e32 v218, 16, v132
	v_and_b32_e32 v219, v71, v132
	v_lshlrev_b32_e32 v220, 16, v104
	v_and_b32_e32 v221, v71, v104
	v_pk_mul_f32 v[218:219], v[178:179], v[218:219]
	v_pk_mul_f32 v[220:221], v[194:195], v[220:221]
	v_cvt_pk_bf16_f32 v224, v218, v219
	v_pk_mul_f32 v[222:223], v[92:93], v[220:221]
	v_cvt_pk_bf16_f32 v225, v220, v221
	ds_write_b32 v94, v224 offset:1088
	ds_write_b32 v94, v225 offset:18496
	v_cvt_pk_bf16_f32 v226, v222, v223
	ds_write_b32 v69, v226 offset:36864
	v_lshlrev_b32_e32 v228, 16, v133
	v_and_b32_e32 v229, v71, v133
	v_lshlrev_b32_e32 v230, 16, v105
	v_and_b32_e32 v231, v71, v105
	v_pk_mul_f32 v[228:229], v[180:181], v[228:229]
	v_pk_mul_f32 v[230:231], v[196:197], v[230:231]
	v_cvt_pk_bf16_f32 v234, v228, v229
	v_pk_mul_f32 v[232:233], v[92:93], v[230:231]
	v_cvt_pk_bf16_f32 v235, v230, v231
	ds_write_b32 v94, v234 offset:1360
	ds_write_b32 v94, v235 offset:18768
	v_cvt_pk_bf16_f32 v236, v232, v233
	ds_write_b32 v69, v236 offset:36928
	v_lshlrev_b32_e32 v218, 16, v134
	v_and_b32_e32 v219, v71, v134
	v_lshlrev_b32_e32 v220, 16, v106
	v_and_b32_e32 v221, v71, v106
	v_pk_mul_f32 v[218:219], v[182:183], v[218:219]
	v_pk_mul_f32 v[220:221], v[198:199], v[220:221]
	v_cvt_pk_bf16_f32 v224, v218, v219
	v_pk_mul_f32 v[222:223], v[92:93], v[220:221]
	v_cvt_pk_bf16_f32 v225, v220, v221
	ds_write_b32 v94, v224 offset:1632
	ds_write_b32 v94, v225 offset:19040
	v_cvt_pk_bf16_f32 v226, v222, v223
	ds_write_b32 v69, v226 offset:36992
	v_lshlrev_b32_e32 v228, 16, v135
	v_and_b32_e32 v229, v71, v135
	v_lshlrev_b32_e32 v230, 16, v107
	v_and_b32_e32 v231, v71, v107
	v_pk_mul_f32 v[228:229], v[184:185], v[228:229]
	v_pk_mul_f32 v[230:231], v[200:201], v[230:231]
	v_cvt_pk_bf16_f32 v234, v228, v229
	v_pk_mul_f32 v[232:233], v[92:93], v[230:231]
	v_cvt_pk_bf16_f32 v235, v230, v231
	ds_write_b32 v94, v234 offset:1904
	ds_write_b32 v94, v235 offset:19312
	v_cvt_pk_bf16_f32 v236, v232, v233
	ds_write_b32 v69, v236 offset:37056
	s_waitcnt vmcnt(0)
	s_add_i32 s58, s5, 1
	s_cmp_eq_u32 s50, 3
	s_cbranch_scc1 .LBB0_435
	v_mbcnt_lo_u32_b32 v64, -1, 0
	v_mbcnt_hi_u32_b32 v64, -1, v64
	s_andn2_b64 vcc, exec, s[6:7]
	v_add_u32_e32 v70, s72, v64
	s_mov_b32 s34, s58
	s_cbranch_vccnz .LBB0_426
	s_cmp_gt_u32 s5, 2
	s_mov_b32 s34, s50
	s_cbranch_scc1 .LBB0_426
	s_sub_i32 s34, 2, s5
